# P4 and P7 tails: deferred weight conversions on 2 of 8 waves of the non-GEMM workgroups (stopwatch: P4 tail 33.3 -> 26.2 us, P7 sample GEMM loop 28.9 -> 22.8 us)
# speedup vs baseline: 1.0032x; 1.0014x over previous
.LBB0_589:
	s_cmp_gt_i32 s96, 16
	s_cselect_b32 s4, 16, 0
	s_cmp_lt_i32 s2, s4
	s_cbranch_scc1 .LBB0_605
	s_sub_i32 s0, s2, s4
	s_lshl_b32 s0, s0, 1
	v_readlane_b32 s1, v255, 5
	s_add_i32 s0, s0, s1
	s_cmp_gt_u32 s1, 1
	s_cbranch_scc1 .LBB0_605
	s_cmpk_gt_u32 s0, 0x1fff
	s_cbranch_scc1 .LBB0_605
	v_and_b32_e32 v2, 28, v160
	v_readlane_b32 s3, v255, 5
	v_lshlrev_b32_e32 v18, 2, v2
	v_lshlrev_b32_e32 v2, 3, v0
	s_lshl_b32 s3, s3, 14
	v_lshrrev_b32_e32 v20, 3, v170
	v_and_b32_e32 v2, 56, v2
	s_add_i32 s3, s3, 0
	v_mul_u32_u24_e32 v3, 0x84, v2
	v_lshlrev_b32_e32 v4, 2, v20
	v_add_u32_e32 v25, s3, v18
	v_add3_u32 v24, s3, v3, v4
	s_lshr_b32 s3, s3, 14
	v_mul_u32_u24_e32 v26, 0x84, v20
	v_mov_b32_e32 v3, 0
	s_sub_i32 s6, s2, s4
	s_lshl1_add_u32 s3, s6, s3
	s_sub_i32 s1, s96, s4
	v_lshlrev_b32_e32 v2, 1, v2
	v_mov_b32_e32 v19, v3
	s_lshl_b32 s3, s3, 5
	s_lshl_b32 s6, s96, 6
	s_lshl_b32 s4, s4, 6
	v_add_u32_e32 v25, v25, v26
	s_lshl_b32 s1, s1, 1
	s_mov_b32 s5, 0
	v_or_b32_e32 v21, 8, v20
	v_or_b32_e32 v22, 16, v20
	v_or_b32_e32 v23, 24, v20
	v_lshl_add_u64 v[4:5], s[78:79], 0, v[2:3]
	s_waitcnt vmcnt(1)
	v_lshl_add_u64 v[6:7], s[82:83], 0, v[2:3]
	v_lshl_add_u64 v[8:9], s[80:81], 0, v[2:3]
	s_waitcnt vmcnt(0)
	v_lshl_add_u64 v[10:11], s[76:77], 0, v[2:3]
	v_lshl_add_u64 v[12:13], s[18:19], 0, v[18:19]
	v_lshl_add_u64 v[14:15], s[46:47], 0, v[18:19]
	v_lshl_add_u64 v[16:17], s[48:49], 0, v[18:19]
	v_lshl_add_u64 v[18:19], s[36:37], 0, v[18:19]
	s_add_i32 s3, s3, 0x58000
	s_sub_i32 s8, s6, s4
	s_mov_b32 s9, 0x40000
	v_add_u32_e32 v26, 0x420, v25
	v_add_u32_e32 v27, 0x428, v25
	v_add_u32_e32 v28, 0x840, v25
	v_add_u32_e32 v29, 0x848, v25
	v_add_u32_e32 v30, 0xc60, v25
	v_add_u32_e32 v31, 0xc68, v25
	v_add_u32_e32 v32, 0x1080, v25
	v_add_u32_e32 v33, 0x1088, v25
	v_add_u32_e32 v34, 0x14a0, v25
	v_add_u32_e32 v35, 0x14a8, v25
	v_add_u32_e32 v36, 0x18c0, v25
	v_add_u32_e32 v37, 0x18c8, v25
	v_add_u32_e32 v38, 0x1ce0, v25
	v_add_u32_e32 v39, 0x1ce8, v25
	s_movk_i32 s10, 0x7fff
	s_mov_b32 s11, 0xffff0000
	s_branch .LBB0_593

.LBB0_844:
	v_readlane_b32 s0, v255, 16
	v_readlane_b32 s1, v255, 17
	s_andn2_b64 vcc, exec, s[0:1]
	s_cbranch_vccnz .LBB0_864
	s_sub_i32 s0, s2, s35
	s_lshl_b32 s0, s0, 1
	v_readlane_b32 s1, v255, 5
	s_add_i32 s0, s0, s1
	s_cmp_gt_u32 s1, 1
	s_cbranch_scc1 .LBB0_864
	s_cmpk_gt_u32 s0, 0xfff
	s_cbranch_scc1 .LBB0_864
	s_waitcnt vmcnt(15)
	v_and_b32_e32 v2, 28, v171
	v_readlane_b32 s1, v255, 5
	s_waitcnt vmcnt(10)
	v_lshlrev_b32_e32 v22, 2, v2
	v_lshlrev_b32_e32 v2, 3, v0
	s_lshl_b32 s1, s1, 14
	v_lshrrev_b32_e32 v24, 3, v170
	v_and_b32_e32 v2, 56, v2
	s_add_i32 s1, s1, 0
	v_mul_u32_u24_e32 v6, 0x84, v2
	v_lshlrev_b32_e32 v7, 2, v24
	s_waitcnt vmcnt(9)
	v_add_u32_e32 v29, s1, v22
	v_readlane_b32 s8, v255, 6
	v_add3_u32 v28, s1, v6, v7
	s_sub_i32 s3, s2, s35
	s_waitcnt vmcnt(8)
	v_mul_u32_u24_e32 v30, 0x84, v24
	v_lshlrev_b32_e32 v2, 1, v2
	v_mov_b32_e32 v3, 0
	v_readlane_b32 s9, v255, 7
	s_lshr_b32 s1, s1, 14
	s_lshl1_add_u32 s3, s3, s1
	s_sub_i32 s0, s96, s35
	v_lshl_add_u64 v[4:5], s[8:9], 0, v[2:3]
	v_mov_b32_e32 v23, v3
	s_add_i32 s1, s3, 0x2c00
	s_lshl_b32 s3, s3, 5
	s_lshl_b32 s6, s96, 6
	s_lshl_b32 s8, s35, 6
	v_add_u32_e32 v29, v29, v30
	s_lshl_b32 s0, s0, 1
	s_mov_b32 s7, 0
	v_or_b32_e32 v25, 8, v24
	v_or_b32_e32 v26, 16, v24
	v_or_b32_e32 v27, 24, v24
	v_lshl_add_u64 v[6:7], s[78:79], 0, v[2:3]
	v_lshl_add_u64 v[8:9], s[82:83], 0, v[2:3]
	v_lshl_add_u64 v[10:11], s[80:81], 0, v[2:3]
	v_lshl_add_u64 v[12:13], s[76:77], 0, v[2:3]
	v_lshl_add_u64 v[14:15], s[22:23], 0, v[22:23]
	v_lshl_add_u64 v[16:17], s[18:19], 0, v[22:23]
	v_lshl_add_u64 v[18:19], s[46:47], 0, v[22:23]
	v_lshl_add_u64 v[20:21], s[48:49], 0, v[22:23]
	v_lshl_add_u64 v[22:23], s[36:37], 0, v[22:23]
	s_add_i32 s3, s3, 0x98000
	s_sub_i32 s10, s6, s8
	v_add_u32_e32 v30, 0x420, v29
	v_add_u32_e32 v31, 0x428, v29
	v_add_u32_e32 v32, 0x840, v29
	v_add_u32_e32 v33, 0x848, v29
	s_waitcnt vmcnt(7)
	v_add_u32_e32 v34, 0xc60, v29
	v_add_u32_e32 v35, 0xc68, v29
	v_add_u32_e32 v36, 0x1080, v29
	v_add_u32_e32 v37, 0x1088, v29
	s_waitcnt vmcnt(6)
	v_add_u32_e32 v38, 0x14a0, v29
	v_add_u32_e32 v39, 0x14a8, v29
	v_add_u32_e32 v40, 0x18c0, v29
	v_add_u32_e32 v41, 0x18c8, v29
	s_waitcnt vmcnt(5)
	v_add_u32_e32 v42, 0x1ce0, v29
	v_add_u32_e32 v43, 0x1ce8, v29
	s_movk_i32 s11, 0x7fff
	s_mov_b32 s16, 0xffff0000
	s_mov_b32 s17, 0x40000
	s_branch .LBB0_848
